# L1 invalidate issued at barrier arrival (overlaps the arrive atomic); XCC-local leader publishes without waiting for it
# speedup vs baseline: 1.0192x; 1.0086x over previous
; __device__ __forceinline__ unsigned xb_ld(unsigned* p)              { return __hip_atomic_load(p, __ATOMIC_RELAXED, __HIP_MEMORY_SCOPE_AGENT); }
; __device__ __forceinline__ unsigned xb_add(unsigned* p, unsigned v) { return __hip_atomic_fetch_add(p, v, __ATOMIC_RELAXED, __HIP_MEMORY_SCOPE_AGENT); }
; #define XB_SPIN(cond, bar) do { unsigned _sp = 0; while (cond) { __builtin_amdgcn_s_sleep(1); \
;     if ((++_sp & 255u) == 0u) { if (xb_ld(&(bar)[XB_TMO])) break; if (_sp > XB_SPIN_CAP) { atomicAdd(&(bar)[XB_TMO], 1u); break; } } } } while (0)
; __device__ __forceinline__ void xcd_barrier(const XcdBarrier& b, int tid) {
;     ...
;         const unsigned old = xb_add(&bar[XB_XSUB(b.x)], 1u);
;         const unsigned gen = old / nloc;
;         if (old + 1u == (gen + 1u) * nloc) {
;             __builtin_amdgcn_fence(__ATOMIC_RELEASE, "agent");
;             asm volatile("s_waitcnt vmcnt(0)" ::: "memory");
;             const unsigned og = xb_add(&bar[XB_TOP], 1u);
;             const unsigned tg = og / nx;
;             if (og + 1u == (tg + 1u) * nx) xb_add(&bar[XB_TOPGEN], 1u);
;             else XB_SPIN(xb_ld(&bar[XB_TOPGEN]) == tg, bar);
;             __builtin_amdgcn_fence(__ATOMIC_ACQUIRE, "agent");
;             xb_add(&bar[XB_XGEN(b.x)], 1u);
;             asm volatile("s_waitcnt vmcnt(0)" ::: "memory");
;         } else {
;             XB_SPIN(xb_ld(&bar[XB_XGEN(b.x)]) == gen, bar);
;             __builtin_amdgcn_fence(__ATOMIC_ACQUIRE, "agent");
;             asm volatile("s_waitcnt vmcnt(0)" ::: "memory");
.LBB0_1021:
	s_mov_b64 s[12:13], exec
	v_mbcnt_lo_u32_b32 v1, s12, 0
	v_mbcnt_hi_u32_b32 v1, s13, v1
	v_cmp_eq_u32_e32 vcc, 0, v1
	s_and_saveexec_b64 s[10:11], vcc
	s_cbranch_execz .LBB0_1023
	s_bcnt1_i32_b64 s4, s[12:13]
	v_readlane_b32 s12, v254, 38
	v_mov_b32_e32 v3, s4
	v_readlane_b32 s13, v254, 39
	s_nop 4
	global_atomic_add v3, v169, v3, s[12:13] sc0
	buffer_inv sc1
.LBB0_1023:
	s_or_b64 exec, exec, s[10:11]
	v_cvt_f32_u32_e32 v4, v2
	s_waitcnt vmcnt(1)
	v_readfirstlane_b32 s4, v3
	v_sub_u32_e32 v3, 0, v2
	v_rcp_iflag_f32_e32 v4, v4
	v_add_u32_e32 v5, s4, v1
	v_mul_f32_e32 v4, 0x4f7ffffe, v4
	v_cvt_u32_f32_e32 v4, v4
	v_mul_lo_u32 v1, v3, v4
	v_mul_hi_u32 v1, v4, v1
	v_add_u32_e32 v1, v4, v1
	v_mul_hi_u32 v1, v5, v1
	v_mul_lo_u32 v3, v1, v2
	v_sub_u32_e32 v3, v5, v3
	v_add_u32_e32 v4, 1, v1
	v_cmp_ge_u32_e32 vcc, v3, v2
	s_nop 1
	v_cndmask_b32_e32 v1, v1, v4, vcc
	v_sub_u32_e32 v4, v3, v2
	v_cndmask_b32_e32 v3, v3, v4, vcc
	v_add_u32_e32 v4, 1, v1
	v_cmp_ge_u32_e32 vcc, v3, v2
	v_add_u32_e32 v3, 1, v5
	s_nop 0
	v_cndmask_b32_e32 v1, v1, v4, vcc
	v_mul_lo_u32 v4, v2, v1
	v_add_u32_e32 v2, v4, v2
	v_cmp_ne_u32_e32 vcc, v3, v2
	s_and_saveexec_b64 s[10:11], vcc
	s_xor_b64 s[10:11], exec, s[10:11]
	s_cbranch_execz .LBB0_1037
	s_nop 0
	v_readlane_b32 s12, v254, 40
	v_readlane_b32 s13, v254, 41
	s_waitcnt lgkmcnt(0)
	s_nop 3
	global_load_dword v0, v169, s[12:13] sc1
	s_waitcnt vmcnt(0)
	v_cmp_eq_u32_e32 vcc, v0, v1
	s_and_saveexec_b64 s[12:13], vcc
	s_cbranch_execz .LBB0_1036
	s_mov_b32 s4, 1
	s_mov_b64 s[14:15], 0
	s_branch .LBB0_1027

; __device__ __forceinline__ unsigned xb_ld(unsigned* p)              { return __hip_atomic_load(p, __ATOMIC_RELAXED, __HIP_MEMORY_SCOPE_AGENT); }
; __device__ __forceinline__ unsigned xb_add(unsigned* p, unsigned v) { return __hip_atomic_fetch_add(p, v, __ATOMIC_RELAXED, __HIP_MEMORY_SCOPE_AGENT); }
; #define XB_SPIN(cond, bar) do { unsigned _sp = 0; while (cond) { __builtin_amdgcn_s_sleep(1); \
;     if ((++_sp & 255u) == 0u) { if (xb_ld(&(bar)[XB_TMO])) break; if (_sp > XB_SPIN_CAP) { atomicAdd(&(bar)[XB_TMO], 1u); break; } } } } while (0)
; __device__ __forceinline__ void xcd_barrier(const XcdBarrier& b, int tid) {
;     ...
;         if (old + 1u == (gen + 1u) * nloc) {
;             __builtin_amdgcn_fence(__ATOMIC_RELEASE, "agent");
;             asm volatile("s_waitcnt vmcnt(0)" ::: "memory");
;             const unsigned og = xb_add(&bar[XB_TOP], 1u);
;             const unsigned tg = og / nx;
;             if (og + 1u == (tg + 1u) * nx) xb_add(&bar[XB_TOPGEN], 1u);
;             else XB_SPIN(xb_ld(&bar[XB_TOPGEN]) == tg, bar);
;             __builtin_amdgcn_fence(__ATOMIC_ACQUIRE, "agent");
;             xb_add(&bar[XB_XGEN(b.x)], 1u);
;             asm volatile("s_waitcnt vmcnt(0)" ::: "memory");
.Llocal_leader:
	s_nop 0
	s_nop 0
	s_mov_b64 s[10:11], exec
	s_mov_b64 s[12:13], exec
	s_branch .LBB0_1055
